# GU K-loop: lagging wave half reads next phase A-fragments during its MFMA segment into a second register set (v212-249), leading half unchanged
# baseline (speedup 1.0000x reference)
.LBB0_573:
	s_ashr_i32 s25, s24, 31
	s_lshl_b64 s[26:27], s[24:25], 19
	s_add_u32 s26, s8, s26
	s_addc_u32 s27, s9, s27
	s_and_b64 s[28:29], s[4:5], exec
	s_cselect_b32 s25, s27, s35
	s_cselect_b32 s49, s26, s34
	s_ashr_i32 s23, s22, 31
	s_lshl_b64 s[28:29], s[22:23], 19
	s_add_u32 s28, s10, s28
	s_addc_u32 s29, s11, s29
	s_and_b64 s[36:37], s[4:5], exec
	s_cselect_b32 s23, s29, s31
	s_cselect_b32 s50, s28, s30
	s_add_u32 s51, s30, 0x100
	s_addc_u32 s52, s31, 0
	s_add_u32 s30, s34, 0x40080
	s_addc_u32 s31, s35, 0
	s_mov_b32 s53, -2
	s_waitcnt lgkmcnt(0)
	s_and_b64 vcc, exec, s[12:13]
	s_cbranch_vccnz .Llag_peel_574
	s_nop 0
	s_add_u32 s34, s30, 0xfffc0080
	s_addc_u32 s35, s31, -1
	s_add_i32 s54, 0, 0x10000
	s_cmp_eq_u32 s53, 12
	s_cselect_b32 s37, s25, s35
	s_cselect_b32 s36, s49, s34
	v_add_u32_e32 v138, s54, v141
	s_cselect_b32 s35, s23, s52
	s_cselect_b32 s34, s50, s51
	s_add_i32 s61, 0, 0x14000
	ds_read_b128 v[144:147], v138
	ds_read_b128 v[148:151], v138 offset:1024
	ds_read_b128 v[152:155], v138 offset:2048
	ds_read_b128 v[156:159], v138 offset:3072
	v_add_u32_e32 v138, s61, v141
	ds_read_b128 v[160:163], v138
	ds_read_b128 v[164:167], v138 offset:1024
	ds_read_b128 v[168:171], v138 offset:2048
	ds_read_b128 v[172:175], v138 offset:3072
	s_add_i32 m0, s40, 0xc000
	ds_read_b128 v[176:179], v143
	ds_read_b128 v[180:183], v143 offset:1024
	ds_read_b128 v[184:187], v143 offset:2048
	ds_read_b128 v[188:191], v143 offset:3072
	ds_read_b128 v[196:199], v143 offset:4096
	ds_read_b128 v[200:203], v143 offset:5120
	ds_read_b128 v[204:207], v143 offset:6144
	ds_read_b128 v[208:211], v143 offset:7168
	global_load_lds_dwordx4 v136, s[30:31]
	s_add_i32 m0, s40, 0xe000
	s_nop 0
	global_load_lds_dwordx4 v134, s[30:31]
	s_waitcnt vmcnt(8)
	s_waitcnt lgkmcnt(0)
	s_barrier
	s_setprio 1
	s_waitcnt lgkmcnt(0)
	v_mfma_f32_16x16x32_bf16 v[124:127], v[144:147], v[176:179], 0
	v_mfma_f32_16x16x32_bf16 v[120:123], v[152:155], v[176:179], 0
	v_mfma_f32_16x16x32_bf16 v[108:111], v[144:147], v[184:187], 0
	v_mfma_f32_16x16x32_bf16 v[104:107], v[152:155], v[184:187], 0
	v_mfma_f32_16x16x32_bf16 v[92:95], v[144:147], v[196:199], 0
	v_mfma_f32_16x16x32_bf16 v[88:91], v[152:155], v[196:199], 0
	v_mfma_f32_16x16x32_bf16 v[76:79], v[144:147], v[204:207], 0
	v_mfma_f32_16x16x32_bf16 v[72:75], v[152:155], v[204:207], 0
	v_mfma_f32_16x16x32_bf16 v[124:127], v[148:151], v[180:183], v[124:127]
	v_mfma_f32_16x16x32_bf16 v[120:123], v[156:159], v[180:183], v[120:123]
	v_mfma_f32_16x16x32_bf16 v[108:111], v[148:151], v[188:191], v[108:111]
	v_mfma_f32_16x16x32_bf16 v[104:107], v[156:159], v[188:191], v[104:107]
	v_mfma_f32_16x16x32_bf16 v[92:95], v[148:151], v[200:203], v[92:95]
	v_mfma_f32_16x16x32_bf16 v[88:91], v[156:159], v[200:203], v[88:91]
	v_mfma_f32_16x16x32_bf16 v[76:79], v[148:151], v[208:211], v[76:79]
	v_mfma_f32_16x16x32_bf16 v[72:75], v[156:159], v[208:211], v[72:75]
	s_setprio 0
	s_setprio 1
	v_mfma_f32_16x16x32_bf16 v[116:119], v[160:163], v[176:179], 0
	v_mfma_f32_16x16x32_bf16 v[112:115], v[168:171], v[176:179], 0
	v_mfma_f32_16x16x32_bf16 v[100:103], v[160:163], v[184:187], 0
	v_mfma_f32_16x16x32_bf16 v[96:99], v[168:171], v[184:187], 0
	v_mfma_f32_16x16x32_bf16 v[84:87], v[160:163], v[196:199], 0
	v_mfma_f32_16x16x32_bf16 v[80:83], v[168:171], v[196:199], 0
	v_mfma_f32_16x16x32_bf16 v[68:71], v[160:163], v[204:207], 0
	v_mfma_f32_16x16x32_bf16 v[64:67], v[168:171], v[204:207], 0
	v_mfma_f32_16x16x32_bf16 v[116:119], v[164:167], v[180:183], v[116:119]
	v_mfma_f32_16x16x32_bf16 v[112:115], v[172:175], v[180:183], v[112:115]
	v_mfma_f32_16x16x32_bf16 v[100:103], v[164:167], v[188:191], v[100:103]
	v_mfma_f32_16x16x32_bf16 v[96:99], v[172:175], v[188:191], v[96:99]
	v_mfma_f32_16x16x32_bf16 v[84:87], v[164:167], v[200:203], v[84:87]
	v_mfma_f32_16x16x32_bf16 v[80:83], v[172:175], v[200:203], v[80:83]
	v_mfma_f32_16x16x32_bf16 v[68:71], v[164:167], v[208:211], v[68:71]
	v_mfma_f32_16x16x32_bf16 v[64:67], v[172:175], v[208:211], v[64:67]
	s_setprio 0
	s_barrier
	s_add_i32 s54, s54, s39
	s_mov_b32 m0, s54
	ds_read_b128 v[176:179], v143 offset:16384
	ds_read_b128 v[180:183], v143 offset:17408
	ds_read_b128 v[184:187], v143 offset:18432
	ds_read_b128 v[188:191], v143 offset:19456
	ds_read_b128 v[196:199], v143 offset:20480
	ds_read_b128 v[200:203], v143 offset:21504
	ds_read_b128 v[204:207], v143 offset:22528
	ds_read_b128 v[208:211], v143 offset:23552
	global_load_lds_dwordx4 v192, s[34:35]
	s_add_i32 m0, s54, 0x2000
	s_add_u32 s54, s34, 0x40000
	s_addc_u32 s55, s35, 0
	s_add_i32 s61, s61, s39
	global_load_lds_dwordx4 v128, s[34:35]
	s_mov_b32 m0, s61
	s_nop 0
	global_load_lds_dwordx4 v192, s[54:55]
	s_add_i32 m0, s61, 0x2000
	s_nop 0
	global_load_lds_dwordx4 v128, s[54:55]
	s_mov_b32 m0, s40
	s_nop 0
	global_load_lds_dwordx4 v132, s[36:37]
	s_mov_b32 m0, s41
	s_nop 0
	global_load_lds_dwordx4 v130, s[36:37]
	s_waitcnt vmcnt(8)
	s_waitcnt lgkmcnt(0)
	s_barrier
	s_setprio 1
	s_waitcnt lgkmcnt(0)
	v_mfma_f32_16x16x32_bf16 v[60:63], v[144:147], v[176:179], 0
	v_mfma_f32_16x16x32_bf16 v[56:59], v[152:155], v[176:179], 0
	v_mfma_f32_16x16x32_bf16 v[44:47], v[144:147], v[184:187], 0
	v_mfma_f32_16x16x32_bf16 v[40:43], v[152:155], v[184:187], 0
	v_mfma_f32_16x16x32_bf16 v[28:31], v[144:147], v[196:199], 0
	v_mfma_f32_16x16x32_bf16 v[24:27], v[152:155], v[196:199], 0
	v_mfma_f32_16x16x32_bf16 v[12:15], v[144:147], v[204:207], 0
	v_mfma_f32_16x16x32_bf16 v[8:11], v[152:155], v[204:207], 0
	v_mfma_f32_16x16x32_bf16 v[60:63], v[148:151], v[180:183], v[60:63]
	v_mfma_f32_16x16x32_bf16 v[56:59], v[156:159], v[180:183], v[56:59]
	v_mfma_f32_16x16x32_bf16 v[44:47], v[148:151], v[188:191], v[44:47]
	v_mfma_f32_16x16x32_bf16 v[40:43], v[156:159], v[188:191], v[40:43]
	v_mfma_f32_16x16x32_bf16 v[28:31], v[148:151], v[200:203], v[28:31]
	v_mfma_f32_16x16x32_bf16 v[24:27], v[156:159], v[200:203], v[24:27]
	v_mfma_f32_16x16x32_bf16 v[12:15], v[148:151], v[208:211], v[12:15]
	v_mfma_f32_16x16x32_bf16 v[8:11], v[156:159], v[208:211], v[8:11]
	s_setprio 0
	s_setprio 1
	v_mfma_f32_16x16x32_bf16 v[52:55], v[160:163], v[176:179], 0
	v_mfma_f32_16x16x32_bf16 v[48:51], v[168:171], v[176:179], 0
	v_mfma_f32_16x16x32_bf16 v[36:39], v[160:163], v[184:187], 0
	v_mfma_f32_16x16x32_bf16 v[32:35], v[168:171], v[184:187], 0
	v_mfma_f32_16x16x32_bf16 v[20:23], v[160:163], v[196:199], 0
	v_mfma_f32_16x16x32_bf16 v[16:19], v[168:171], v[196:199], 0
	v_mfma_f32_16x16x32_bf16 v[4:7], v[160:163], v[204:207], 0
	v_mfma_f32_16x16x32_bf16 v[0:3], v[168:171], v[204:207], 0
	v_mfma_f32_16x16x32_bf16 v[52:55], v[164:167], v[180:183], v[52:55]
	v_mfma_f32_16x16x32_bf16 v[48:51], v[172:175], v[180:183], v[48:51]
	v_mfma_f32_16x16x32_bf16 v[36:39], v[164:167], v[188:191], v[36:39]
	v_mfma_f32_16x16x32_bf16 v[32:35], v[172:175], v[188:191], v[32:35]
	v_mfma_f32_16x16x32_bf16 v[20:23], v[164:167], v[200:203], v[20:23]
	v_mfma_f32_16x16x32_bf16 v[16:19], v[172:175], v[200:203], v[16:19]
	v_mfma_f32_16x16x32_bf16 v[4:7], v[164:167], v[208:211], v[4:7]
	v_mfma_f32_16x16x32_bf16 v[0:3], v[172:175], v[208:211], v[0:3]
	s_setprio 0
	s_barrier
	s_nop 0
	s_add_i32 s54, 0, 0x18000
	s_add_i32 s55, 0, 0x1c000
	v_add_u32_e32 v156, s54, v141
	v_add_u32_e32 v172, s55, v141
	ds_read_b128 v[144:147], v156
	ds_read_b128 v[148:151], v156 offset:1024
	ds_read_b128 v[152:155], v156 offset:2048
	ds_read_b128 v[156:159], v156 offset:3072
	ds_read_b128 v[160:163], v172
	ds_read_b128 v[164:167], v172 offset:1024
	ds_read_b128 v[168:171], v172 offset:2048
	ds_read_b128 v[172:175], v172 offset:3072
	s_add_u32 s36, s36, 0x40000
	s_addc_u32 s37, s37, 0
	s_mov_b32 m0, s42
	ds_read_b128 v[176:179], v143 offset:32768
	ds_read_b128 v[180:183], v143 offset:33792
	ds_read_b128 v[184:187], v143 offset:34816
	ds_read_b128 v[188:191], v143 offset:35840
	ds_read_b128 v[196:199], v143 offset:36864
	ds_read_b128 v[200:203], v143 offset:37888
	ds_read_b128 v[204:207], v143 offset:38912
	ds_read_b128 v[208:211], v143 offset:39936
	global_load_lds_dwordx4 v132, s[36:37]
	s_mov_b32 m0, s43
	s_nop 0
	global_load_lds_dwordx4 v130, s[36:37]
	s_waitcnt vmcnt(8)
	s_waitcnt lgkmcnt(0)
	s_barrier
	s_setprio 1
	s_waitcnt lgkmcnt(0)
	v_mfma_f32_16x16x32_bf16 v[124:127], v[144:147], v[176:179], v[124:127]
	v_mfma_f32_16x16x32_bf16 v[120:123], v[152:155], v[176:179], v[120:123]
	v_mfma_f32_16x16x32_bf16 v[108:111], v[144:147], v[184:187], v[108:111]
	v_mfma_f32_16x16x32_bf16 v[104:107], v[152:155], v[184:187], v[104:107]
	v_mfma_f32_16x16x32_bf16 v[92:95], v[144:147], v[196:199], v[92:95]
	v_mfma_f32_16x16x32_bf16 v[88:91], v[152:155], v[196:199], v[88:91]
	v_mfma_f32_16x16x32_bf16 v[76:79], v[144:147], v[204:207], v[76:79]
	v_mfma_f32_16x16x32_bf16 v[72:75], v[152:155], v[204:207], v[72:75]
	v_mfma_f32_16x16x32_bf16 v[124:127], v[148:151], v[180:183], v[124:127]
	v_mfma_f32_16x16x32_bf16 v[120:123], v[156:159], v[180:183], v[120:123]
	v_mfma_f32_16x16x32_bf16 v[108:111], v[148:151], v[188:191], v[108:111]
	v_mfma_f32_16x16x32_bf16 v[104:107], v[156:159], v[188:191], v[104:107]
	v_mfma_f32_16x16x32_bf16 v[92:95], v[148:151], v[200:203], v[92:95]
	v_mfma_f32_16x16x32_bf16 v[88:91], v[156:159], v[200:203], v[88:91]
	v_mfma_f32_16x16x32_bf16 v[76:79], v[148:151], v[208:211], v[76:79]
	v_mfma_f32_16x16x32_bf16 v[72:75], v[156:159], v[208:211], v[72:75]
	s_setprio 0
	s_setprio 1
	v_mfma_f32_16x16x32_bf16 v[116:119], v[160:163], v[176:179], v[116:119]
	v_mfma_f32_16x16x32_bf16 v[112:115], v[168:171], v[176:179], v[112:115]
	v_mfma_f32_16x16x32_bf16 v[100:103], v[160:163], v[184:187], v[100:103]
	v_mfma_f32_16x16x32_bf16 v[96:99], v[168:171], v[184:187], v[96:99]
	v_mfma_f32_16x16x32_bf16 v[84:87], v[160:163], v[196:199], v[84:87]
	v_mfma_f32_16x16x32_bf16 v[80:83], v[168:171], v[196:199], v[80:83]
	v_mfma_f32_16x16x32_bf16 v[68:71], v[160:163], v[204:207], v[68:71]
	v_mfma_f32_16x16x32_bf16 v[64:67], v[168:171], v[204:207], v[64:67]
	v_mfma_f32_16x16x32_bf16 v[116:119], v[164:167], v[180:183], v[116:119]
	v_mfma_f32_16x16x32_bf16 v[112:115], v[172:175], v[180:183], v[112:115]
	v_mfma_f32_16x16x32_bf16 v[100:103], v[164:167], v[188:191], v[100:103]
	v_mfma_f32_16x16x32_bf16 v[96:99], v[172:175], v[188:191], v[96:99]
	v_mfma_f32_16x16x32_bf16 v[84:87], v[164:167], v[200:203], v[84:87]
	v_mfma_f32_16x16x32_bf16 v[80:83], v[172:175], v[200:203], v[80:83]
	v_mfma_f32_16x16x32_bf16 v[68:71], v[164:167], v[208:211], v[68:71]
	v_mfma_f32_16x16x32_bf16 v[64:67], v[172:175], v[208:211], v[64:67]
	s_setprio 0
	s_barrier
	s_nop 0
	s_add_u32 s36, s36, 0xfffc0080
	s_addc_u32 s37, s37, -1
	s_add_u32 s34, s34, 0x80
	s_addc_u32 s35, s35, 0
	s_add_i32 m0, s54, s39
	ds_read_b128 v[176:179], v143 offset:49152
	ds_read_b128 v[180:183], v143 offset:50176
	ds_read_b128 v[184:187], v143 offset:51200
	ds_read_b128 v[188:191], v143 offset:52224
	ds_read_b128 v[196:199], v143 offset:53248
	ds_read_b128 v[200:203], v143 offset:54272
	ds_read_b128 v[204:207], v143 offset:55296
	ds_read_b128 v[208:211], v143 offset:56320
	global_load_lds_dwordx4 v192, s[34:35]
	s_add_i32 m0, m0, 0x2000
	s_nop 0
	global_load_lds_dwordx4 v128, s[34:35]
	s_add_u32 s34, s34, 0x40000
	s_addc_u32 s35, s35, 0
	s_add_i32 m0, s55, s39
	s_nop 0
	global_load_lds_dwordx4 v192, s[34:35]
	s_add_i32 m0, m0, 0x2000
	s_nop 0
	global_load_lds_dwordx4 v128, s[34:35]
	s_mov_b32 m0, s44
	s_nop 0
	global_load_lds_dwordx4 v132, s[36:37]
	s_mov_b32 m0, s45
	s_nop 0
	global_load_lds_dwordx4 v130, s[36:37]
	s_waitcnt vmcnt(8)
	s_waitcnt lgkmcnt(0)
	s_barrier
	s_setprio 1
	s_waitcnt lgkmcnt(0)
	v_mfma_f32_16x16x32_bf16 v[60:63], v[144:147], v[176:179], v[60:63]
	v_mfma_f32_16x16x32_bf16 v[56:59], v[152:155], v[176:179], v[56:59]
	v_mfma_f32_16x16x32_bf16 v[44:47], v[144:147], v[184:187], v[44:47]
	v_mfma_f32_16x16x32_bf16 v[40:43], v[152:155], v[184:187], v[40:43]
	v_mfma_f32_16x16x32_bf16 v[28:31], v[144:147], v[196:199], v[28:31]
	v_mfma_f32_16x16x32_bf16 v[24:27], v[152:155], v[196:199], v[24:27]
	v_mfma_f32_16x16x32_bf16 v[12:15], v[144:147], v[204:207], v[12:15]
	v_mfma_f32_16x16x32_bf16 v[8:11], v[152:155], v[204:207], v[8:11]
	v_mfma_f32_16x16x32_bf16 v[60:63], v[148:151], v[180:183], v[60:63]
	v_mfma_f32_16x16x32_bf16 v[56:59], v[156:159], v[180:183], v[56:59]
	v_mfma_f32_16x16x32_bf16 v[44:47], v[148:151], v[188:191], v[44:47]
	v_mfma_f32_16x16x32_bf16 v[40:43], v[156:159], v[188:191], v[40:43]
	v_mfma_f32_16x16x32_bf16 v[28:31], v[148:151], v[200:203], v[28:31]
	v_mfma_f32_16x16x32_bf16 v[24:27], v[156:159], v[200:203], v[24:27]
	v_mfma_f32_16x16x32_bf16 v[12:15], v[148:151], v[208:211], v[12:15]
	v_mfma_f32_16x16x32_bf16 v[8:11], v[156:159], v[208:211], v[8:11]
	s_setprio 0
	s_setprio 1
	v_mfma_f32_16x16x32_bf16 v[52:55], v[160:163], v[176:179], v[52:55]
	v_mfma_f32_16x16x32_bf16 v[48:51], v[168:171], v[176:179], v[48:51]
	v_mfma_f32_16x16x32_bf16 v[36:39], v[160:163], v[184:187], v[36:39]
	v_mfma_f32_16x16x32_bf16 v[32:35], v[168:171], v[184:187], v[32:35]
	v_mfma_f32_16x16x32_bf16 v[20:23], v[160:163], v[196:199], v[20:23]
	v_mfma_f32_16x16x32_bf16 v[16:19], v[168:171], v[196:199], v[16:19]
	v_mfma_f32_16x16x32_bf16 v[4:7], v[160:163], v[204:207], v[4:7]
	v_mfma_f32_16x16x32_bf16 v[0:3], v[168:171], v[204:207], v[0:3]
	v_mfma_f32_16x16x32_bf16 v[52:55], v[164:167], v[180:183], v[52:55]
	v_mfma_f32_16x16x32_bf16 v[48:51], v[172:175], v[180:183], v[48:51]
	v_mfma_f32_16x16x32_bf16 v[36:39], v[164:167], v[188:191], v[36:39]
	v_mfma_f32_16x16x32_bf16 v[32:35], v[172:175], v[188:191], v[32:35]
	v_mfma_f32_16x16x32_bf16 v[20:23], v[164:167], v[200:203], v[20:23]
	v_mfma_f32_16x16x32_bf16 v[16:19], v[172:175], v[200:203], v[16:19]
	v_mfma_f32_16x16x32_bf16 v[4:7], v[164:167], v[208:211], v[4:7]
	v_mfma_f32_16x16x32_bf16 v[0:3], v[172:175], v[208:211], v[0:3]
	s_setprio 0
	s_barrier
	s_add_i32 s53, s53, 2
	s_add_u32 s51, s51, 0x100
	s_addc_u32 s52, s52, 0
	s_add_u32 s30, s30, 0x100
	s_addc_u32 s31, s31, 0
	s_cmp_gt_u32 s53, 13
	s_cbranch_scc0 .LBB0_574
	s_branch .Lpeel_exit_574
.LBB0_574:
	s_nop 0
	s_add_u32 s34, s30, 0xfffc0080
	s_addc_u32 s35, s31, -1
	s_add_i32 s54, 0, 0x10000
	s_cmp_eq_u32 s53, 12
	s_cselect_b32 s37, s25, s35
	s_cselect_b32 s36, s49, s34
	v_add_u32_e32 v138, s54, v141
	s_cselect_b32 s35, s23, s52
	s_cselect_b32 s34, s50, s51
	s_add_i32 s61, 0, 0x14000
	ds_read_b128 v[144:147], v138
	ds_read_b128 v[148:151], v138 offset:1024
	ds_read_b128 v[152:155], v138 offset:2048
	ds_read_b128 v[156:159], v138 offset:3072
	v_add_u32_e32 v138, s61, v141
	ds_read_b128 v[160:163], v138
	ds_read_b128 v[164:167], v138 offset:1024
	ds_read_b128 v[168:171], v138 offset:2048
	ds_read_b128 v[172:175], v138 offset:3072
	s_add_i32 m0, s40, 0xc000
	ds_read_b128 v[176:179], v143
	ds_read_b128 v[180:183], v143 offset:1024
	ds_read_b128 v[184:187], v143 offset:2048
	ds_read_b128 v[188:191], v143 offset:3072
	ds_read_b128 v[196:199], v143 offset:4096
	ds_read_b128 v[200:203], v143 offset:5120
	ds_read_b128 v[204:207], v143 offset:6144
	ds_read_b128 v[208:211], v143 offset:7168
	global_load_lds_dwordx4 v136, s[30:31]
	s_add_i32 m0, s40, 0xe000
	s_nop 0
	global_load_lds_dwordx4 v134, s[30:31]
	s_waitcnt vmcnt(8)
	s_waitcnt lgkmcnt(0)
	s_barrier
	s_setprio 1
	s_waitcnt lgkmcnt(0)
	v_mfma_f32_16x16x32_bf16 v[124:127], v[144:147], v[176:179], v[124:127]
	v_mfma_f32_16x16x32_bf16 v[120:123], v[152:155], v[176:179], v[120:123]
	v_mfma_f32_16x16x32_bf16 v[108:111], v[144:147], v[184:187], v[108:111]
	v_mfma_f32_16x16x32_bf16 v[104:107], v[152:155], v[184:187], v[104:107]
	v_mfma_f32_16x16x32_bf16 v[92:95], v[144:147], v[196:199], v[92:95]
	v_mfma_f32_16x16x32_bf16 v[88:91], v[152:155], v[196:199], v[88:91]
	v_mfma_f32_16x16x32_bf16 v[76:79], v[144:147], v[204:207], v[76:79]
	v_mfma_f32_16x16x32_bf16 v[72:75], v[152:155], v[204:207], v[72:75]
	v_mfma_f32_16x16x32_bf16 v[124:127], v[148:151], v[180:183], v[124:127]
	v_mfma_f32_16x16x32_bf16 v[120:123], v[156:159], v[180:183], v[120:123]
	v_mfma_f32_16x16x32_bf16 v[108:111], v[148:151], v[188:191], v[108:111]
	v_mfma_f32_16x16x32_bf16 v[104:107], v[156:159], v[188:191], v[104:107]
	v_mfma_f32_16x16x32_bf16 v[92:95], v[148:151], v[200:203], v[92:95]
	v_mfma_f32_16x16x32_bf16 v[88:91], v[156:159], v[200:203], v[88:91]
	v_mfma_f32_16x16x32_bf16 v[76:79], v[148:151], v[208:211], v[76:79]
	v_mfma_f32_16x16x32_bf16 v[72:75], v[156:159], v[208:211], v[72:75]
	s_setprio 0
	s_setprio 1
	v_mfma_f32_16x16x32_bf16 v[116:119], v[160:163], v[176:179], v[116:119]
	v_mfma_f32_16x16x32_bf16 v[112:115], v[168:171], v[176:179], v[112:115]
	v_mfma_f32_16x16x32_bf16 v[100:103], v[160:163], v[184:187], v[100:103]
	v_mfma_f32_16x16x32_bf16 v[96:99], v[168:171], v[184:187], v[96:99]
	v_mfma_f32_16x16x32_bf16 v[84:87], v[160:163], v[196:199], v[84:87]
	v_mfma_f32_16x16x32_bf16 v[80:83], v[168:171], v[196:199], v[80:83]
	v_mfma_f32_16x16x32_bf16 v[68:71], v[160:163], v[204:207], v[68:71]
	v_mfma_f32_16x16x32_bf16 v[64:67], v[168:171], v[204:207], v[64:67]
	v_mfma_f32_16x16x32_bf16 v[116:119], v[164:167], v[180:183], v[116:119]
	v_mfma_f32_16x16x32_bf16 v[112:115], v[172:175], v[180:183], v[112:115]
	v_mfma_f32_16x16x32_bf16 v[100:103], v[164:167], v[188:191], v[100:103]
	v_mfma_f32_16x16x32_bf16 v[96:99], v[172:175], v[188:191], v[96:99]
	v_mfma_f32_16x16x32_bf16 v[84:87], v[164:167], v[200:203], v[84:87]
	v_mfma_f32_16x16x32_bf16 v[80:83], v[172:175], v[200:203], v[80:83]
	v_mfma_f32_16x16x32_bf16 v[68:71], v[164:167], v[208:211], v[68:71]
	v_mfma_f32_16x16x32_bf16 v[64:67], v[172:175], v[208:211], v[64:67]
	s_setprio 0
	s_barrier
	s_add_i32 s54, s54, s39
	s_mov_b32 m0, s54
	ds_read_b128 v[176:179], v143 offset:16384
	ds_read_b128 v[180:183], v143 offset:17408
	ds_read_b128 v[184:187], v143 offset:18432
	ds_read_b128 v[188:191], v143 offset:19456
	ds_read_b128 v[196:199], v143 offset:20480
	ds_read_b128 v[200:203], v143 offset:21504
	ds_read_b128 v[204:207], v143 offset:22528
	ds_read_b128 v[208:211], v143 offset:23552
	global_load_lds_dwordx4 v192, s[34:35]
	s_add_i32 m0, s54, 0x2000
	s_add_u32 s54, s34, 0x40000
	s_addc_u32 s55, s35, 0
	s_add_i32 s61, s61, s39
	global_load_lds_dwordx4 v128, s[34:35]
	s_mov_b32 m0, s61
	s_nop 0
	global_load_lds_dwordx4 v192, s[54:55]
	s_add_i32 m0, s61, 0x2000
	s_nop 0
	global_load_lds_dwordx4 v128, s[54:55]
	s_mov_b32 m0, s40
	s_nop 0
	global_load_lds_dwordx4 v132, s[36:37]
	s_mov_b32 m0, s41
	s_nop 0
	global_load_lds_dwordx4 v130, s[36:37]
	s_waitcnt vmcnt(8)
	s_waitcnt lgkmcnt(0)
	s_barrier
	s_setprio 1
	s_waitcnt lgkmcnt(0)
	v_mfma_f32_16x16x32_bf16 v[60:63], v[144:147], v[176:179], v[60:63]
	v_mfma_f32_16x16x32_bf16 v[56:59], v[152:155], v[176:179], v[56:59]
	v_mfma_f32_16x16x32_bf16 v[44:47], v[144:147], v[184:187], v[44:47]
	v_mfma_f32_16x16x32_bf16 v[40:43], v[152:155], v[184:187], v[40:43]
	v_mfma_f32_16x16x32_bf16 v[28:31], v[144:147], v[196:199], v[28:31]
	v_mfma_f32_16x16x32_bf16 v[24:27], v[152:155], v[196:199], v[24:27]
	v_mfma_f32_16x16x32_bf16 v[12:15], v[144:147], v[204:207], v[12:15]
	v_mfma_f32_16x16x32_bf16 v[8:11], v[152:155], v[204:207], v[8:11]
	v_mfma_f32_16x16x32_bf16 v[60:63], v[148:151], v[180:183], v[60:63]
	v_mfma_f32_16x16x32_bf16 v[56:59], v[156:159], v[180:183], v[56:59]
	v_mfma_f32_16x16x32_bf16 v[44:47], v[148:151], v[188:191], v[44:47]
	v_mfma_f32_16x16x32_bf16 v[40:43], v[156:159], v[188:191], v[40:43]
	v_mfma_f32_16x16x32_bf16 v[28:31], v[148:151], v[200:203], v[28:31]
	v_mfma_f32_16x16x32_bf16 v[24:27], v[156:159], v[200:203], v[24:27]
	v_mfma_f32_16x16x32_bf16 v[12:15], v[148:151], v[208:211], v[12:15]
	v_mfma_f32_16x16x32_bf16 v[8:11], v[156:159], v[208:211], v[8:11]
	s_setprio 0
	s_setprio 1
	v_mfma_f32_16x16x32_bf16 v[52:55], v[160:163], v[176:179], v[52:55]
	v_mfma_f32_16x16x32_bf16 v[48:51], v[168:171], v[176:179], v[48:51]
	v_mfma_f32_16x16x32_bf16 v[36:39], v[160:163], v[184:187], v[36:39]
	v_mfma_f32_16x16x32_bf16 v[32:35], v[168:171], v[184:187], v[32:35]
	v_mfma_f32_16x16x32_bf16 v[20:23], v[160:163], v[196:199], v[20:23]
	v_mfma_f32_16x16x32_bf16 v[16:19], v[168:171], v[196:199], v[16:19]
	v_mfma_f32_16x16x32_bf16 v[4:7], v[160:163], v[204:207], v[4:7]
	v_mfma_f32_16x16x32_bf16 v[0:3], v[168:171], v[204:207], v[0:3]
	v_mfma_f32_16x16x32_bf16 v[52:55], v[164:167], v[180:183], v[52:55]
	v_mfma_f32_16x16x32_bf16 v[48:51], v[172:175], v[180:183], v[48:51]
	v_mfma_f32_16x16x32_bf16 v[36:39], v[164:167], v[188:191], v[36:39]
	v_mfma_f32_16x16x32_bf16 v[32:35], v[172:175], v[188:191], v[32:35]
	v_mfma_f32_16x16x32_bf16 v[20:23], v[164:167], v[200:203], v[20:23]
	v_mfma_f32_16x16x32_bf16 v[16:19], v[172:175], v[200:203], v[16:19]
	v_mfma_f32_16x16x32_bf16 v[4:7], v[164:167], v[208:211], v[4:7]
	v_mfma_f32_16x16x32_bf16 v[0:3], v[172:175], v[208:211], v[0:3]
	s_setprio 0
	s_barrier
	s_nop 0
	s_add_i32 s54, 0, 0x18000
	s_add_i32 s55, 0, 0x1c000
	v_add_u32_e32 v156, s54, v141
	v_add_u32_e32 v172, s55, v141
	ds_read_b128 v[144:147], v156
	ds_read_b128 v[148:151], v156 offset:1024
	ds_read_b128 v[152:155], v156 offset:2048
	ds_read_b128 v[156:159], v156 offset:3072
	ds_read_b128 v[160:163], v172
	ds_read_b128 v[164:167], v172 offset:1024
	ds_read_b128 v[168:171], v172 offset:2048
	ds_read_b128 v[172:175], v172 offset:3072
	s_add_u32 s36, s36, 0x40000
	s_addc_u32 s37, s37, 0
	s_mov_b32 m0, s42
	ds_read_b128 v[176:179], v143 offset:32768
	ds_read_b128 v[180:183], v143 offset:33792
	ds_read_b128 v[184:187], v143 offset:34816
	ds_read_b128 v[188:191], v143 offset:35840
	ds_read_b128 v[196:199], v143 offset:36864
	ds_read_b128 v[200:203], v143 offset:37888
	ds_read_b128 v[204:207], v143 offset:38912
	ds_read_b128 v[208:211], v143 offset:39936
	global_load_lds_dwordx4 v132, s[36:37]
	s_mov_b32 m0, s43
	s_nop 0
	global_load_lds_dwordx4 v130, s[36:37]
	s_waitcnt vmcnt(8)
	s_waitcnt lgkmcnt(0)
	s_barrier
	s_setprio 1
	s_waitcnt lgkmcnt(0)
	v_mfma_f32_16x16x32_bf16 v[124:127], v[144:147], v[176:179], v[124:127]
	v_mfma_f32_16x16x32_bf16 v[120:123], v[152:155], v[176:179], v[120:123]
	v_mfma_f32_16x16x32_bf16 v[108:111], v[144:147], v[184:187], v[108:111]
	v_mfma_f32_16x16x32_bf16 v[104:107], v[152:155], v[184:187], v[104:107]
	v_mfma_f32_16x16x32_bf16 v[92:95], v[144:147], v[196:199], v[92:95]
	v_mfma_f32_16x16x32_bf16 v[88:91], v[152:155], v[196:199], v[88:91]
	v_mfma_f32_16x16x32_bf16 v[76:79], v[144:147], v[204:207], v[76:79]
	v_mfma_f32_16x16x32_bf16 v[72:75], v[152:155], v[204:207], v[72:75]
	v_mfma_f32_16x16x32_bf16 v[124:127], v[148:151], v[180:183], v[124:127]
	v_mfma_f32_16x16x32_bf16 v[120:123], v[156:159], v[180:183], v[120:123]
	v_mfma_f32_16x16x32_bf16 v[108:111], v[148:151], v[188:191], v[108:111]
	v_mfma_f32_16x16x32_bf16 v[104:107], v[156:159], v[188:191], v[104:107]
	v_mfma_f32_16x16x32_bf16 v[92:95], v[148:151], v[200:203], v[92:95]
	v_mfma_f32_16x16x32_bf16 v[88:91], v[156:159], v[200:203], v[88:91]
	v_mfma_f32_16x16x32_bf16 v[76:79], v[148:151], v[208:211], v[76:79]
	v_mfma_f32_16x16x32_bf16 v[72:75], v[156:159], v[208:211], v[72:75]
	s_setprio 0
	s_setprio 1
	v_mfma_f32_16x16x32_bf16 v[116:119], v[160:163], v[176:179], v[116:119]
	v_mfma_f32_16x16x32_bf16 v[112:115], v[168:171], v[176:179], v[112:115]
	v_mfma_f32_16x16x32_bf16 v[100:103], v[160:163], v[184:187], v[100:103]
	v_mfma_f32_16x16x32_bf16 v[96:99], v[168:171], v[184:187], v[96:99]
	v_mfma_f32_16x16x32_bf16 v[84:87], v[160:163], v[196:199], v[84:87]
	v_mfma_f32_16x16x32_bf16 v[80:83], v[168:171], v[196:199], v[80:83]
	v_mfma_f32_16x16x32_bf16 v[68:71], v[160:163], v[204:207], v[68:71]
	v_mfma_f32_16x16x32_bf16 v[64:67], v[168:171], v[204:207], v[64:67]
	v_mfma_f32_16x16x32_bf16 v[116:119], v[164:167], v[180:183], v[116:119]
	v_mfma_f32_16x16x32_bf16 v[112:115], v[172:175], v[180:183], v[112:115]
	v_mfma_f32_16x16x32_bf16 v[100:103], v[164:167], v[188:191], v[100:103]
	v_mfma_f32_16x16x32_bf16 v[96:99], v[172:175], v[188:191], v[96:99]
	v_mfma_f32_16x16x32_bf16 v[84:87], v[164:167], v[200:203], v[84:87]
	v_mfma_f32_16x16x32_bf16 v[80:83], v[172:175], v[200:203], v[80:83]
	v_mfma_f32_16x16x32_bf16 v[68:71], v[164:167], v[208:211], v[68:71]
	v_mfma_f32_16x16x32_bf16 v[64:67], v[172:175], v[208:211], v[64:67]
	s_setprio 0
	s_barrier
	s_nop 0
	s_add_u32 s36, s36, 0xfffc0080
	s_addc_u32 s37, s37, -1
	s_add_u32 s34, s34, 0x80
	s_addc_u32 s35, s35, 0
	s_add_i32 m0, s54, s39
	ds_read_b128 v[176:179], v143 offset:49152
	ds_read_b128 v[180:183], v143 offset:50176
	ds_read_b128 v[184:187], v143 offset:51200
	ds_read_b128 v[188:191], v143 offset:52224
	ds_read_b128 v[196:199], v143 offset:53248
	ds_read_b128 v[200:203], v143 offset:54272
	ds_read_b128 v[204:207], v143 offset:55296
	ds_read_b128 v[208:211], v143 offset:56320
	global_load_lds_dwordx4 v192, s[34:35]
	s_add_i32 m0, m0, 0x2000
	s_nop 0
	global_load_lds_dwordx4 v128, s[34:35]
	s_add_u32 s34, s34, 0x40000
	s_addc_u32 s35, s35, 0
	s_add_i32 m0, s55, s39
	s_nop 0
	global_load_lds_dwordx4 v192, s[34:35]
	s_add_i32 m0, m0, 0x2000
	s_nop 0
	global_load_lds_dwordx4 v128, s[34:35]
	s_mov_b32 m0, s44
	s_nop 0
	global_load_lds_dwordx4 v132, s[36:37]
	s_mov_b32 m0, s45
	s_nop 0
	global_load_lds_dwordx4 v130, s[36:37]
	s_waitcnt vmcnt(8)
	s_waitcnt lgkmcnt(0)
	s_barrier
	s_setprio 1
	s_waitcnt lgkmcnt(0)
	v_mfma_f32_16x16x32_bf16 v[60:63], v[144:147], v[176:179], v[60:63]
	v_mfma_f32_16x16x32_bf16 v[56:59], v[152:155], v[176:179], v[56:59]
	v_mfma_f32_16x16x32_bf16 v[44:47], v[144:147], v[184:187], v[44:47]
	v_mfma_f32_16x16x32_bf16 v[40:43], v[152:155], v[184:187], v[40:43]
	v_mfma_f32_16x16x32_bf16 v[28:31], v[144:147], v[196:199], v[28:31]
	v_mfma_f32_16x16x32_bf16 v[24:27], v[152:155], v[196:199], v[24:27]
	v_mfma_f32_16x16x32_bf16 v[12:15], v[144:147], v[204:207], v[12:15]
	v_mfma_f32_16x16x32_bf16 v[8:11], v[152:155], v[204:207], v[8:11]
	v_mfma_f32_16x16x32_bf16 v[60:63], v[148:151], v[180:183], v[60:63]
	v_mfma_f32_16x16x32_bf16 v[56:59], v[156:159], v[180:183], v[56:59]
	v_mfma_f32_16x16x32_bf16 v[44:47], v[148:151], v[188:191], v[44:47]
	v_mfma_f32_16x16x32_bf16 v[40:43], v[156:159], v[188:191], v[40:43]
	v_mfma_f32_16x16x32_bf16 v[28:31], v[148:151], v[200:203], v[28:31]
	v_mfma_f32_16x16x32_bf16 v[24:27], v[156:159], v[200:203], v[24:27]
	v_mfma_f32_16x16x32_bf16 v[12:15], v[148:151], v[208:211], v[12:15]
	v_mfma_f32_16x16x32_bf16 v[8:11], v[156:159], v[208:211], v[8:11]
	s_setprio 0
	s_setprio 1
	v_mfma_f32_16x16x32_bf16 v[52:55], v[160:163], v[176:179], v[52:55]
	v_mfma_f32_16x16x32_bf16 v[48:51], v[168:171], v[176:179], v[48:51]
	v_mfma_f32_16x16x32_bf16 v[36:39], v[160:163], v[184:187], v[36:39]
	v_mfma_f32_16x16x32_bf16 v[32:35], v[168:171], v[184:187], v[32:35]
	v_mfma_f32_16x16x32_bf16 v[20:23], v[160:163], v[196:199], v[20:23]
	v_mfma_f32_16x16x32_bf16 v[16:19], v[168:171], v[196:199], v[16:19]
	v_mfma_f32_16x16x32_bf16 v[4:7], v[160:163], v[204:207], v[4:7]
	v_mfma_f32_16x16x32_bf16 v[0:3], v[168:171], v[204:207], v[0:3]
	v_mfma_f32_16x16x32_bf16 v[52:55], v[164:167], v[180:183], v[52:55]
	v_mfma_f32_16x16x32_bf16 v[48:51], v[172:175], v[180:183], v[48:51]
	v_mfma_f32_16x16x32_bf16 v[36:39], v[164:167], v[188:191], v[36:39]
	v_mfma_f32_16x16x32_bf16 v[32:35], v[172:175], v[188:191], v[32:35]
	v_mfma_f32_16x16x32_bf16 v[20:23], v[164:167], v[200:203], v[20:23]
	v_mfma_f32_16x16x32_bf16 v[16:19], v[172:175], v[200:203], v[16:19]
	v_mfma_f32_16x16x32_bf16 v[4:7], v[164:167], v[208:211], v[4:7]
	v_mfma_f32_16x16x32_bf16 v[0:3], v[172:175], v[208:211], v[0:3]
	s_setprio 0
	s_barrier
	s_add_i32 s53, s53, 2
	s_add_u32 s51, s51, 0x100
	s_addc_u32 s52, s52, 0
	s_add_u32 s30, s30, 0x100
	s_addc_u32 s31, s31, 0
	s_cmp_gt_u32 s53, 13
	s_cbranch_scc0 .LBB0_574
	s_branch .Lpeel_exit_574
.Llag_peel_574:
	s_nop 0
	s_add_u32 s34, s30, 0xfffc0080
	s_addc_u32 s35, s31, -1
	s_add_i32 s54, 0, 0x10000
	s_cmp_eq_u32 s53, 12
	s_cselect_b32 s37, s25, s35
	s_cselect_b32 s36, s49, s34
	v_add_u32_e32 v138, s54, v141
	s_cselect_b32 s35, s23, s52
	s_cselect_b32 s34, s50, s51
	s_add_i32 s61, 0, 0x14000
	ds_read_b128 v[144:147], v138
	ds_read_b128 v[148:151], v138 offset:1024
	ds_read_b128 v[152:155], v138 offset:2048
	ds_read_b128 v[156:159], v138 offset:3072
	v_add_u32_e32 v138, s61, v141
	ds_read_b128 v[160:163], v138
	ds_read_b128 v[164:167], v138 offset:1024
	ds_read_b128 v[168:171], v138 offset:2048
	ds_read_b128 v[172:175], v138 offset:3072
	s_add_i32 m0, s40, 0xc000
	ds_read_b128 v[176:179], v143
	ds_read_b128 v[180:183], v143 offset:1024
	ds_read_b128 v[184:187], v143 offset:2048
	ds_read_b128 v[188:191], v143 offset:3072
	ds_read_b128 v[196:199], v143 offset:4096
	ds_read_b128 v[200:203], v143 offset:5120
	ds_read_b128 v[204:207], v143 offset:6144
	ds_read_b128 v[208:211], v143 offset:7168
	global_load_lds_dwordx4 v136, s[30:31]
	s_add_i32 m0, s40, 0xe000
	s_nop 0
	global_load_lds_dwordx4 v134, s[30:31]
	s_waitcnt vmcnt(8)
	s_waitcnt lgkmcnt(0)
	s_barrier
	s_setprio 1
	s_waitcnt lgkmcnt(0)
	v_mfma_f32_16x16x32_bf16 v[124:127], v[144:147], v[176:179], 0
	v_mfma_f32_16x16x32_bf16 v[120:123], v[152:155], v[176:179], 0
	ds_read_b128 v[212:215], v143 offset:16384
	v_mfma_f32_16x16x32_bf16 v[108:111], v[144:147], v[184:187], 0
	v_mfma_f32_16x16x32_bf16 v[104:107], v[152:155], v[184:187], 0
	v_mfma_f32_16x16x32_bf16 v[92:95], v[144:147], v[196:199], 0
	v_mfma_f32_16x16x32_bf16 v[88:91], v[152:155], v[196:199], 0
	ds_read_b128 v[216:219], v143 offset:17408
	v_mfma_f32_16x16x32_bf16 v[76:79], v[144:147], v[204:207], 0
	v_mfma_f32_16x16x32_bf16 v[72:75], v[152:155], v[204:207], 0
	v_mfma_f32_16x16x32_bf16 v[124:127], v[148:151], v[180:183], v[124:127]
	v_mfma_f32_16x16x32_bf16 v[120:123], v[156:159], v[180:183], v[120:123]
	ds_read_b128 v[220:223], v143 offset:18432
	v_mfma_f32_16x16x32_bf16 v[108:111], v[148:151], v[188:191], v[108:111]
	v_mfma_f32_16x16x32_bf16 v[104:107], v[156:159], v[188:191], v[104:107]
	v_mfma_f32_16x16x32_bf16 v[92:95], v[148:151], v[200:203], v[92:95]
	v_mfma_f32_16x16x32_bf16 v[88:91], v[156:159], v[200:203], v[88:91]
	ds_read_b128 v[224:227], v143 offset:19456
	v_mfma_f32_16x16x32_bf16 v[76:79], v[148:151], v[208:211], v[76:79]
	v_mfma_f32_16x16x32_bf16 v[72:75], v[156:159], v[208:211], v[72:75]
	s_setprio 0
	s_setprio 1
	v_mfma_f32_16x16x32_bf16 v[116:119], v[160:163], v[176:179], 0
	v_mfma_f32_16x16x32_bf16 v[112:115], v[168:171], v[176:179], 0
	ds_read_b128 v[232:235], v143 offset:20480
	v_mfma_f32_16x16x32_bf16 v[100:103], v[160:163], v[184:187], 0
	v_mfma_f32_16x16x32_bf16 v[96:99], v[168:171], v[184:187], 0
	v_mfma_f32_16x16x32_bf16 v[84:87], v[160:163], v[196:199], 0
	v_mfma_f32_16x16x32_bf16 v[80:83], v[168:171], v[196:199], 0
	ds_read_b128 v[238:241], v143 offset:21504
	v_mfma_f32_16x16x32_bf16 v[68:71], v[160:163], v[204:207], 0
	v_mfma_f32_16x16x32_bf16 v[64:67], v[168:171], v[204:207], 0
	v_mfma_f32_16x16x32_bf16 v[116:119], v[164:167], v[180:183], v[116:119]
	v_mfma_f32_16x16x32_bf16 v[112:115], v[172:175], v[180:183], v[112:115]
	ds_read_b128 v[242:245], v143 offset:22528
	v_mfma_f32_16x16x32_bf16 v[100:103], v[164:167], v[188:191], v[100:103]
	v_mfma_f32_16x16x32_bf16 v[96:99], v[172:175], v[188:191], v[96:99]
	v_mfma_f32_16x16x32_bf16 v[84:87], v[164:167], v[200:203], v[84:87]
	v_mfma_f32_16x16x32_bf16 v[80:83], v[172:175], v[200:203], v[80:83]
	ds_read_b128 v[246:249], v143 offset:23552
	v_mfma_f32_16x16x32_bf16 v[68:71], v[164:167], v[208:211], v[68:71]
	v_mfma_f32_16x16x32_bf16 v[64:67], v[172:175], v[208:211], v[64:67]
	s_setprio 0
	s_barrier
	s_add_i32 s54, s54, s39
	s_mov_b32 m0, s54
	s_nop 0
	global_load_lds_dwordx4 v192, s[34:35]
	s_add_i32 m0, s54, 0x2000
	s_add_u32 s54, s34, 0x40000
	s_addc_u32 s55, s35, 0
	s_add_i32 s61, s61, s39
	global_load_lds_dwordx4 v128, s[34:35]
	s_mov_b32 m0, s61
	s_nop 0
	global_load_lds_dwordx4 v192, s[54:55]
	s_add_i32 m0, s61, 0x2000
	s_nop 0
	global_load_lds_dwordx4 v128, s[54:55]
	s_mov_b32 m0, s40
	s_nop 0
	global_load_lds_dwordx4 v132, s[36:37]
	s_mov_b32 m0, s41
	s_nop 0
	global_load_lds_dwordx4 v130, s[36:37]
	s_waitcnt vmcnt(8)
	s_waitcnt lgkmcnt(0)
	s_barrier
	s_setprio 1
	s_waitcnt lgkmcnt(0)
	v_mfma_f32_16x16x32_bf16 v[60:63], v[144:147], v[212:215], 0
	v_mfma_f32_16x16x32_bf16 v[56:59], v[152:155], v[212:215], 0
	ds_read_b128 v[176:179], v143 offset:32768
	v_mfma_f32_16x16x32_bf16 v[44:47], v[144:147], v[220:223], 0
	v_mfma_f32_16x16x32_bf16 v[40:43], v[152:155], v[220:223], 0
	v_mfma_f32_16x16x32_bf16 v[28:31], v[144:147], v[232:235], 0
	v_mfma_f32_16x16x32_bf16 v[24:27], v[152:155], v[232:235], 0
	ds_read_b128 v[180:183], v143 offset:33792
	v_mfma_f32_16x16x32_bf16 v[12:15], v[144:147], v[242:245], 0
	v_mfma_f32_16x16x32_bf16 v[8:11], v[152:155], v[242:245], 0
	v_mfma_f32_16x16x32_bf16 v[60:63], v[148:151], v[216:219], v[60:63]
	v_mfma_f32_16x16x32_bf16 v[56:59], v[156:159], v[216:219], v[56:59]
	ds_read_b128 v[184:187], v143 offset:34816
	v_mfma_f32_16x16x32_bf16 v[44:47], v[148:151], v[224:227], v[44:47]
	v_mfma_f32_16x16x32_bf16 v[40:43], v[156:159], v[224:227], v[40:43]
	v_mfma_f32_16x16x32_bf16 v[28:31], v[148:151], v[238:241], v[28:31]
	v_mfma_f32_16x16x32_bf16 v[24:27], v[156:159], v[238:241], v[24:27]
	ds_read_b128 v[188:191], v143 offset:35840
	v_mfma_f32_16x16x32_bf16 v[12:15], v[148:151], v[246:249], v[12:15]
	v_mfma_f32_16x16x32_bf16 v[8:11], v[156:159], v[246:249], v[8:11]
	s_setprio 0
	s_setprio 1
	v_mfma_f32_16x16x32_bf16 v[52:55], v[160:163], v[212:215], 0
	v_mfma_f32_16x16x32_bf16 v[48:51], v[168:171], v[212:215], 0
	ds_read_b128 v[196:199], v143 offset:36864
	v_mfma_f32_16x16x32_bf16 v[36:39], v[160:163], v[220:223], 0
	v_mfma_f32_16x16x32_bf16 v[32:35], v[168:171], v[220:223], 0
	v_mfma_f32_16x16x32_bf16 v[20:23], v[160:163], v[232:235], 0
	v_mfma_f32_16x16x32_bf16 v[16:19], v[168:171], v[232:235], 0
	ds_read_b128 v[200:203], v143 offset:37888
	v_mfma_f32_16x16x32_bf16 v[4:7], v[160:163], v[242:245], 0
	v_mfma_f32_16x16x32_bf16 v[0:3], v[168:171], v[242:245], 0
	v_mfma_f32_16x16x32_bf16 v[52:55], v[164:167], v[216:219], v[52:55]
	v_mfma_f32_16x16x32_bf16 v[48:51], v[172:175], v[216:219], v[48:51]
	ds_read_b128 v[204:207], v143 offset:38912
	v_mfma_f32_16x16x32_bf16 v[36:39], v[164:167], v[224:227], v[36:39]
	v_mfma_f32_16x16x32_bf16 v[32:35], v[172:175], v[224:227], v[32:35]
	v_mfma_f32_16x16x32_bf16 v[20:23], v[164:167], v[238:241], v[20:23]
	v_mfma_f32_16x16x32_bf16 v[16:19], v[172:175], v[238:241], v[16:19]
	ds_read_b128 v[208:211], v143 offset:39936
	v_mfma_f32_16x16x32_bf16 v[4:7], v[164:167], v[246:249], v[4:7]
	v_mfma_f32_16x16x32_bf16 v[0:3], v[172:175], v[246:249], v[0:3]
	s_setprio 0
	s_barrier
	s_nop 0
	s_add_i32 s54, 0, 0x18000
	s_add_i32 s55, 0, 0x1c000
	v_add_u32_e32 v156, s54, v141
	v_add_u32_e32 v172, s55, v141
	ds_read_b128 v[144:147], v156
	ds_read_b128 v[148:151], v156 offset:1024
	ds_read_b128 v[152:155], v156 offset:2048
	ds_read_b128 v[156:159], v156 offset:3072
	ds_read_b128 v[160:163], v172
	ds_read_b128 v[164:167], v172 offset:1024
	ds_read_b128 v[168:171], v172 offset:2048
	ds_read_b128 v[172:175], v172 offset:3072
	s_add_u32 s36, s36, 0x40000
	s_addc_u32 s37, s37, 0
	s_mov_b32 m0, s42
	s_nop 0
	global_load_lds_dwordx4 v132, s[36:37]
	s_mov_b32 m0, s43
	s_nop 0
	global_load_lds_dwordx4 v130, s[36:37]
	s_waitcnt vmcnt(8)
	s_waitcnt lgkmcnt(0)
	s_barrier
	s_setprio 1
	s_waitcnt lgkmcnt(0)
	v_mfma_f32_16x16x32_bf16 v[124:127], v[144:147], v[176:179], v[124:127]
	v_mfma_f32_16x16x32_bf16 v[120:123], v[152:155], v[176:179], v[120:123]
	ds_read_b128 v[212:215], v143 offset:49152
	v_mfma_f32_16x16x32_bf16 v[108:111], v[144:147], v[184:187], v[108:111]
	v_mfma_f32_16x16x32_bf16 v[104:107], v[152:155], v[184:187], v[104:107]
	v_mfma_f32_16x16x32_bf16 v[92:95], v[144:147], v[196:199], v[92:95]
	v_mfma_f32_16x16x32_bf16 v[88:91], v[152:155], v[196:199], v[88:91]
	ds_read_b128 v[216:219], v143 offset:50176
	v_mfma_f32_16x16x32_bf16 v[76:79], v[144:147], v[204:207], v[76:79]
	v_mfma_f32_16x16x32_bf16 v[72:75], v[152:155], v[204:207], v[72:75]
	v_mfma_f32_16x16x32_bf16 v[124:127], v[148:151], v[180:183], v[124:127]
	v_mfma_f32_16x16x32_bf16 v[120:123], v[156:159], v[180:183], v[120:123]
	ds_read_b128 v[220:223], v143 offset:51200
	v_mfma_f32_16x16x32_bf16 v[108:111], v[148:151], v[188:191], v[108:111]
	v_mfma_f32_16x16x32_bf16 v[104:107], v[156:159], v[188:191], v[104:107]
	v_mfma_f32_16x16x32_bf16 v[92:95], v[148:151], v[200:203], v[92:95]
	v_mfma_f32_16x16x32_bf16 v[88:91], v[156:159], v[200:203], v[88:91]
	ds_read_b128 v[224:227], v143 offset:52224
	v_mfma_f32_16x16x32_bf16 v[76:79], v[148:151], v[208:211], v[76:79]
	v_mfma_f32_16x16x32_bf16 v[72:75], v[156:159], v[208:211], v[72:75]
	s_setprio 0
	s_setprio 1
	v_mfma_f32_16x16x32_bf16 v[116:119], v[160:163], v[176:179], v[116:119]
	v_mfma_f32_16x16x32_bf16 v[112:115], v[168:171], v[176:179], v[112:115]
	ds_read_b128 v[232:235], v143 offset:53248
	v_mfma_f32_16x16x32_bf16 v[100:103], v[160:163], v[184:187], v[100:103]
	v_mfma_f32_16x16x32_bf16 v[96:99], v[168:171], v[184:187], v[96:99]
	v_mfma_f32_16x16x32_bf16 v[84:87], v[160:163], v[196:199], v[84:87]
	v_mfma_f32_16x16x32_bf16 v[80:83], v[168:171], v[196:199], v[80:83]
	ds_read_b128 v[238:241], v143 offset:54272
	v_mfma_f32_16x16x32_bf16 v[68:71], v[160:163], v[204:207], v[68:71]
	v_mfma_f32_16x16x32_bf16 v[64:67], v[168:171], v[204:207], v[64:67]
	v_mfma_f32_16x16x32_bf16 v[116:119], v[164:167], v[180:183], v[116:119]
	v_mfma_f32_16x16x32_bf16 v[112:115], v[172:175], v[180:183], v[112:115]
	ds_read_b128 v[242:245], v143 offset:55296
	v_mfma_f32_16x16x32_bf16 v[100:103], v[164:167], v[188:191], v[100:103]
	v_mfma_f32_16x16x32_bf16 v[96:99], v[172:175], v[188:191], v[96:99]
	v_mfma_f32_16x16x32_bf16 v[84:87], v[164:167], v[200:203], v[84:87]
	v_mfma_f32_16x16x32_bf16 v[80:83], v[172:175], v[200:203], v[80:83]
	ds_read_b128 v[246:249], v143 offset:56320
	v_mfma_f32_16x16x32_bf16 v[68:71], v[164:167], v[208:211], v[68:71]
	v_mfma_f32_16x16x32_bf16 v[64:67], v[172:175], v[208:211], v[64:67]
	s_setprio 0
	s_barrier
	s_nop 0
	s_add_u32 s36, s36, 0xfffc0080
	s_addc_u32 s37, s37, -1
	s_add_u32 s34, s34, 0x80
	s_addc_u32 s35, s35, 0
	s_add_i32 m0, s54, s39
	s_nop 0
	global_load_lds_dwordx4 v192, s[34:35]
	s_add_i32 m0, m0, 0x2000
	s_nop 0
	global_load_lds_dwordx4 v128, s[34:35]
	s_add_u32 s34, s34, 0x40000
	s_addc_u32 s35, s35, 0
	s_add_i32 m0, s55, s39
	s_nop 0
	global_load_lds_dwordx4 v192, s[34:35]
	s_add_i32 m0, m0, 0x2000
	s_nop 0
	global_load_lds_dwordx4 v128, s[34:35]
	s_mov_b32 m0, s44
	s_nop 0
	global_load_lds_dwordx4 v132, s[36:37]
	s_mov_b32 m0, s45
	s_nop 0
	global_load_lds_dwordx4 v130, s[36:37]
	s_waitcnt vmcnt(8)
	s_waitcnt lgkmcnt(0)
	s_barrier
	s_setprio 1
	s_waitcnt lgkmcnt(0)
	v_mfma_f32_16x16x32_bf16 v[60:63], v[144:147], v[212:215], v[60:63]
	v_mfma_f32_16x16x32_bf16 v[56:59], v[152:155], v[212:215], v[56:59]
	ds_read_b128 v[176:179], v143
	v_mfma_f32_16x16x32_bf16 v[44:47], v[144:147], v[220:223], v[44:47]
	v_mfma_f32_16x16x32_bf16 v[40:43], v[152:155], v[220:223], v[40:43]
	v_mfma_f32_16x16x32_bf16 v[28:31], v[144:147], v[232:235], v[28:31]
	v_mfma_f32_16x16x32_bf16 v[24:27], v[152:155], v[232:235], v[24:27]
	ds_read_b128 v[180:183], v143 offset:1024
	v_mfma_f32_16x16x32_bf16 v[12:15], v[144:147], v[242:245], v[12:15]
	v_mfma_f32_16x16x32_bf16 v[8:11], v[152:155], v[242:245], v[8:11]
	v_mfma_f32_16x16x32_bf16 v[60:63], v[148:151], v[216:219], v[60:63]
	v_mfma_f32_16x16x32_bf16 v[56:59], v[156:159], v[216:219], v[56:59]
	ds_read_b128 v[184:187], v143 offset:2048
	v_mfma_f32_16x16x32_bf16 v[44:47], v[148:151], v[224:227], v[44:47]
	v_mfma_f32_16x16x32_bf16 v[40:43], v[156:159], v[224:227], v[40:43]
	v_mfma_f32_16x16x32_bf16 v[28:31], v[148:151], v[238:241], v[28:31]
	v_mfma_f32_16x16x32_bf16 v[24:27], v[156:159], v[238:241], v[24:27]
	ds_read_b128 v[188:191], v143 offset:3072
	v_mfma_f32_16x16x32_bf16 v[12:15], v[148:151], v[246:249], v[12:15]
	v_mfma_f32_16x16x32_bf16 v[8:11], v[156:159], v[246:249], v[8:11]
	s_setprio 0
	s_setprio 1
	v_mfma_f32_16x16x32_bf16 v[52:55], v[160:163], v[212:215], v[52:55]
	v_mfma_f32_16x16x32_bf16 v[48:51], v[168:171], v[212:215], v[48:51]
	ds_read_b128 v[196:199], v143 offset:4096
	v_mfma_f32_16x16x32_bf16 v[36:39], v[160:163], v[220:223], v[36:39]
	v_mfma_f32_16x16x32_bf16 v[32:35], v[168:171], v[220:223], v[32:35]
	v_mfma_f32_16x16x32_bf16 v[20:23], v[160:163], v[232:235], v[20:23]
	v_mfma_f32_16x16x32_bf16 v[16:19], v[168:171], v[232:235], v[16:19]
	ds_read_b128 v[200:203], v143 offset:5120
	v_mfma_f32_16x16x32_bf16 v[4:7], v[160:163], v[242:245], v[4:7]
	v_mfma_f32_16x16x32_bf16 v[0:3], v[168:171], v[242:245], v[0:3]
	v_mfma_f32_16x16x32_bf16 v[52:55], v[164:167], v[216:219], v[52:55]
	v_mfma_f32_16x16x32_bf16 v[48:51], v[172:175], v[216:219], v[48:51]
	ds_read_b128 v[204:207], v143 offset:6144
	v_mfma_f32_16x16x32_bf16 v[36:39], v[164:167], v[224:227], v[36:39]
	v_mfma_f32_16x16x32_bf16 v[32:35], v[172:175], v[224:227], v[32:35]
	v_mfma_f32_16x16x32_bf16 v[20:23], v[164:167], v[238:241], v[20:23]
	v_mfma_f32_16x16x32_bf16 v[16:19], v[172:175], v[238:241], v[16:19]
	ds_read_b128 v[208:211], v143 offset:7168
	v_mfma_f32_16x16x32_bf16 v[4:7], v[164:167], v[246:249], v[4:7]
	v_mfma_f32_16x16x32_bf16 v[0:3], v[172:175], v[246:249], v[0:3]
	s_setprio 0
	s_barrier
	s_add_i32 s53, s53, 2
	s_add_u32 s51, s51, 0x100
	s_addc_u32 s52, s52, 0
	s_add_u32 s30, s30, 0x100
	s_addc_u32 s31, s31, 0
	s_cmp_gt_u32 s53, 13
	s_cbranch_scc0 .Llag_574
	s_branch .Llag_exit_574
.Llag_574:
	s_nop 0
	s_add_u32 s34, s30, 0xfffc0080
	s_addc_u32 s35, s31, -1
	s_add_i32 s54, 0, 0x10000
	s_cmp_eq_u32 s53, 12
	s_cselect_b32 s37, s25, s35
	s_cselect_b32 s36, s49, s34
	v_add_u32_e32 v138, s54, v141
	s_cselect_b32 s35, s23, s52
	s_cselect_b32 s34, s50, s51
	s_add_i32 s61, 0, 0x14000
	ds_read_b128 v[144:147], v138
	ds_read_b128 v[148:151], v138 offset:1024
	ds_read_b128 v[152:155], v138 offset:2048
	ds_read_b128 v[156:159], v138 offset:3072
	v_add_u32_e32 v138, s61, v141
	ds_read_b128 v[160:163], v138
	ds_read_b128 v[164:167], v138 offset:1024
	ds_read_b128 v[168:171], v138 offset:2048
	ds_read_b128 v[172:175], v138 offset:3072
	s_add_i32 m0, s40, 0xc000
	s_nop 0
	global_load_lds_dwordx4 v136, s[30:31]
	s_add_i32 m0, s40, 0xe000
	s_nop 0
	global_load_lds_dwordx4 v134, s[30:31]
	s_waitcnt vmcnt(8)
	s_waitcnt lgkmcnt(0)
	s_barrier
	s_setprio 1
	s_waitcnt lgkmcnt(0)
	v_mfma_f32_16x16x32_bf16 v[124:127], v[144:147], v[176:179], v[124:127]
	v_mfma_f32_16x16x32_bf16 v[120:123], v[152:155], v[176:179], v[120:123]
	ds_read_b128 v[212:215], v143 offset:16384
	v_mfma_f32_16x16x32_bf16 v[108:111], v[144:147], v[184:187], v[108:111]
	v_mfma_f32_16x16x32_bf16 v[104:107], v[152:155], v[184:187], v[104:107]
	v_mfma_f32_16x16x32_bf16 v[92:95], v[144:147], v[196:199], v[92:95]
	v_mfma_f32_16x16x32_bf16 v[88:91], v[152:155], v[196:199], v[88:91]
	ds_read_b128 v[216:219], v143 offset:17408
	v_mfma_f32_16x16x32_bf16 v[76:79], v[144:147], v[204:207], v[76:79]
	v_mfma_f32_16x16x32_bf16 v[72:75], v[152:155], v[204:207], v[72:75]
	v_mfma_f32_16x16x32_bf16 v[124:127], v[148:151], v[180:183], v[124:127]
	v_mfma_f32_16x16x32_bf16 v[120:123], v[156:159], v[180:183], v[120:123]
	ds_read_b128 v[220:223], v143 offset:18432
	v_mfma_f32_16x16x32_bf16 v[108:111], v[148:151], v[188:191], v[108:111]
	v_mfma_f32_16x16x32_bf16 v[104:107], v[156:159], v[188:191], v[104:107]
	v_mfma_f32_16x16x32_bf16 v[92:95], v[148:151], v[200:203], v[92:95]
	v_mfma_f32_16x16x32_bf16 v[88:91], v[156:159], v[200:203], v[88:91]
	ds_read_b128 v[224:227], v143 offset:19456
	v_mfma_f32_16x16x32_bf16 v[76:79], v[148:151], v[208:211], v[76:79]
	v_mfma_f32_16x16x32_bf16 v[72:75], v[156:159], v[208:211], v[72:75]
	s_setprio 0
	s_setprio 1
	v_mfma_f32_16x16x32_bf16 v[116:119], v[160:163], v[176:179], v[116:119]
	v_mfma_f32_16x16x32_bf16 v[112:115], v[168:171], v[176:179], v[112:115]
	ds_read_b128 v[232:235], v143 offset:20480
	v_mfma_f32_16x16x32_bf16 v[100:103], v[160:163], v[184:187], v[100:103]
	v_mfma_f32_16x16x32_bf16 v[96:99], v[168:171], v[184:187], v[96:99]
	v_mfma_f32_16x16x32_bf16 v[84:87], v[160:163], v[196:199], v[84:87]
	v_mfma_f32_16x16x32_bf16 v[80:83], v[168:171], v[196:199], v[80:83]
	ds_read_b128 v[238:241], v143 offset:21504
	v_mfma_f32_16x16x32_bf16 v[68:71], v[160:163], v[204:207], v[68:71]
	v_mfma_f32_16x16x32_bf16 v[64:67], v[168:171], v[204:207], v[64:67]
	v_mfma_f32_16x16x32_bf16 v[116:119], v[164:167], v[180:183], v[116:119]
	v_mfma_f32_16x16x32_bf16 v[112:115], v[172:175], v[180:183], v[112:115]
	ds_read_b128 v[242:245], v143 offset:22528
	v_mfma_f32_16x16x32_bf16 v[100:103], v[164:167], v[188:191], v[100:103]
	v_mfma_f32_16x16x32_bf16 v[96:99], v[172:175], v[188:191], v[96:99]
	v_mfma_f32_16x16x32_bf16 v[84:87], v[164:167], v[200:203], v[84:87]
	v_mfma_f32_16x16x32_bf16 v[80:83], v[172:175], v[200:203], v[80:83]
	ds_read_b128 v[246:249], v143 offset:23552
	v_mfma_f32_16x16x32_bf16 v[68:71], v[164:167], v[208:211], v[68:71]
	v_mfma_f32_16x16x32_bf16 v[64:67], v[172:175], v[208:211], v[64:67]
	s_setprio 0
	s_barrier
	s_add_i32 s54, s54, s39
	s_mov_b32 m0, s54
	s_nop 0
	global_load_lds_dwordx4 v192, s[34:35]
	s_add_i32 m0, s54, 0x2000
	s_add_u32 s54, s34, 0x40000
	s_addc_u32 s55, s35, 0
	s_add_i32 s61, s61, s39
	global_load_lds_dwordx4 v128, s[34:35]
	s_mov_b32 m0, s61
	s_nop 0
	global_load_lds_dwordx4 v192, s[54:55]
	s_add_i32 m0, s61, 0x2000
	s_nop 0
	global_load_lds_dwordx4 v128, s[54:55]
	s_mov_b32 m0, s40
	s_nop 0
	global_load_lds_dwordx4 v132, s[36:37]
	s_mov_b32 m0, s41
	s_nop 0
	global_load_lds_dwordx4 v130, s[36:37]
	s_waitcnt vmcnt(8)
	s_waitcnt lgkmcnt(0)
	s_barrier
	s_setprio 1
	s_waitcnt lgkmcnt(0)
	v_mfma_f32_16x16x32_bf16 v[60:63], v[144:147], v[212:215], v[60:63]
	v_mfma_f32_16x16x32_bf16 v[56:59], v[152:155], v[212:215], v[56:59]
	ds_read_b128 v[176:179], v143 offset:32768
	v_mfma_f32_16x16x32_bf16 v[44:47], v[144:147], v[220:223], v[44:47]
	v_mfma_f32_16x16x32_bf16 v[40:43], v[152:155], v[220:223], v[40:43]
	v_mfma_f32_16x16x32_bf16 v[28:31], v[144:147], v[232:235], v[28:31]
	v_mfma_f32_16x16x32_bf16 v[24:27], v[152:155], v[232:235], v[24:27]
	ds_read_b128 v[180:183], v143 offset:33792
	v_mfma_f32_16x16x32_bf16 v[12:15], v[144:147], v[242:245], v[12:15]
	v_mfma_f32_16x16x32_bf16 v[8:11], v[152:155], v[242:245], v[8:11]
	v_mfma_f32_16x16x32_bf16 v[60:63], v[148:151], v[216:219], v[60:63]
	v_mfma_f32_16x16x32_bf16 v[56:59], v[156:159], v[216:219], v[56:59]
	ds_read_b128 v[184:187], v143 offset:34816
	v_mfma_f32_16x16x32_bf16 v[44:47], v[148:151], v[224:227], v[44:47]
	v_mfma_f32_16x16x32_bf16 v[40:43], v[156:159], v[224:227], v[40:43]
	v_mfma_f32_16x16x32_bf16 v[28:31], v[148:151], v[238:241], v[28:31]
	v_mfma_f32_16x16x32_bf16 v[24:27], v[156:159], v[238:241], v[24:27]
	ds_read_b128 v[188:191], v143 offset:35840
	v_mfma_f32_16x16x32_bf16 v[12:15], v[148:151], v[246:249], v[12:15]
	v_mfma_f32_16x16x32_bf16 v[8:11], v[156:159], v[246:249], v[8:11]
	s_setprio 0
	s_setprio 1
	v_mfma_f32_16x16x32_bf16 v[52:55], v[160:163], v[212:215], v[52:55]
	v_mfma_f32_16x16x32_bf16 v[48:51], v[168:171], v[212:215], v[48:51]
	ds_read_b128 v[196:199], v143 offset:36864
	v_mfma_f32_16x16x32_bf16 v[36:39], v[160:163], v[220:223], v[36:39]
	v_mfma_f32_16x16x32_bf16 v[32:35], v[168:171], v[220:223], v[32:35]
	v_mfma_f32_16x16x32_bf16 v[20:23], v[160:163], v[232:235], v[20:23]
	v_mfma_f32_16x16x32_bf16 v[16:19], v[168:171], v[232:235], v[16:19]
	ds_read_b128 v[200:203], v143 offset:37888
	v_mfma_f32_16x16x32_bf16 v[4:7], v[160:163], v[242:245], v[4:7]
	v_mfma_f32_16x16x32_bf16 v[0:3], v[168:171], v[242:245], v[0:3]
	v_mfma_f32_16x16x32_bf16 v[52:55], v[164:167], v[216:219], v[52:55]
	v_mfma_f32_16x16x32_bf16 v[48:51], v[172:175], v[216:219], v[48:51]
	ds_read_b128 v[204:207], v143 offset:38912
	v_mfma_f32_16x16x32_bf16 v[36:39], v[164:167], v[224:227], v[36:39]
	v_mfma_f32_16x16x32_bf16 v[32:35], v[172:175], v[224:227], v[32:35]
	v_mfma_f32_16x16x32_bf16 v[20:23], v[164:167], v[238:241], v[20:23]
	v_mfma_f32_16x16x32_bf16 v[16:19], v[172:175], v[238:241], v[16:19]
	ds_read_b128 v[208:211], v143 offset:39936
	v_mfma_f32_16x16x32_bf16 v[4:7], v[164:167], v[246:249], v[4:7]
	v_mfma_f32_16x16x32_bf16 v[0:3], v[172:175], v[246:249], v[0:3]
	s_setprio 0
	s_barrier
	s_nop 0
	s_add_i32 s54, 0, 0x18000
	s_add_i32 s55, 0, 0x1c000
	v_add_u32_e32 v156, s54, v141
	v_add_u32_e32 v172, s55, v141
	ds_read_b128 v[144:147], v156
	ds_read_b128 v[148:151], v156 offset:1024
	ds_read_b128 v[152:155], v156 offset:2048
	ds_read_b128 v[156:159], v156 offset:3072
	ds_read_b128 v[160:163], v172
	ds_read_b128 v[164:167], v172 offset:1024
	ds_read_b128 v[168:171], v172 offset:2048
	ds_read_b128 v[172:175], v172 offset:3072
	s_add_u32 s36, s36, 0x40000
	s_addc_u32 s37, s37, 0
	s_mov_b32 m0, s42
	s_nop 0
	global_load_lds_dwordx4 v132, s[36:37]
	s_mov_b32 m0, s43
	s_nop 0
	global_load_lds_dwordx4 v130, s[36:37]
	s_waitcnt vmcnt(8)
	s_waitcnt lgkmcnt(0)
	s_barrier
	s_setprio 1
	s_waitcnt lgkmcnt(0)
	v_mfma_f32_16x16x32_bf16 v[124:127], v[144:147], v[176:179], v[124:127]
	v_mfma_f32_16x16x32_bf16 v[120:123], v[152:155], v[176:179], v[120:123]
	ds_read_b128 v[212:215], v143 offset:49152
	v_mfma_f32_16x16x32_bf16 v[108:111], v[144:147], v[184:187], v[108:111]
	v_mfma_f32_16x16x32_bf16 v[104:107], v[152:155], v[184:187], v[104:107]
	v_mfma_f32_16x16x32_bf16 v[92:95], v[144:147], v[196:199], v[92:95]
	v_mfma_f32_16x16x32_bf16 v[88:91], v[152:155], v[196:199], v[88:91]
	ds_read_b128 v[216:219], v143 offset:50176
	v_mfma_f32_16x16x32_bf16 v[76:79], v[144:147], v[204:207], v[76:79]
	v_mfma_f32_16x16x32_bf16 v[72:75], v[152:155], v[204:207], v[72:75]
	v_mfma_f32_16x16x32_bf16 v[124:127], v[148:151], v[180:183], v[124:127]
	v_mfma_f32_16x16x32_bf16 v[120:123], v[156:159], v[180:183], v[120:123]
	ds_read_b128 v[220:223], v143 offset:51200
	v_mfma_f32_16x16x32_bf16 v[108:111], v[148:151], v[188:191], v[108:111]
	v_mfma_f32_16x16x32_bf16 v[104:107], v[156:159], v[188:191], v[104:107]
	v_mfma_f32_16x16x32_bf16 v[92:95], v[148:151], v[200:203], v[92:95]
	v_mfma_f32_16x16x32_bf16 v[88:91], v[156:159], v[200:203], v[88:91]
	ds_read_b128 v[224:227], v143 offset:52224
	v_mfma_f32_16x16x32_bf16 v[76:79], v[148:151], v[208:211], v[76:79]
	v_mfma_f32_16x16x32_bf16 v[72:75], v[156:159], v[208:211], v[72:75]
	s_setprio 0
	s_setprio 1
	v_mfma_f32_16x16x32_bf16 v[116:119], v[160:163], v[176:179], v[116:119]
	v_mfma_f32_16x16x32_bf16 v[112:115], v[168:171], v[176:179], v[112:115]
	ds_read_b128 v[232:235], v143 offset:53248
	v_mfma_f32_16x16x32_bf16 v[100:103], v[160:163], v[184:187], v[100:103]
	v_mfma_f32_16x16x32_bf16 v[96:99], v[168:171], v[184:187], v[96:99]
	v_mfma_f32_16x16x32_bf16 v[84:87], v[160:163], v[196:199], v[84:87]
	v_mfma_f32_16x16x32_bf16 v[80:83], v[168:171], v[196:199], v[80:83]
	ds_read_b128 v[238:241], v143 offset:54272
	v_mfma_f32_16x16x32_bf16 v[68:71], v[160:163], v[204:207], v[68:71]
	v_mfma_f32_16x16x32_bf16 v[64:67], v[168:171], v[204:207], v[64:67]
	v_mfma_f32_16x16x32_bf16 v[116:119], v[164:167], v[180:183], v[116:119]
	v_mfma_f32_16x16x32_bf16 v[112:115], v[172:175], v[180:183], v[112:115]
	ds_read_b128 v[242:245], v143 offset:55296
	v_mfma_f32_16x16x32_bf16 v[100:103], v[164:167], v[188:191], v[100:103]
	v_mfma_f32_16x16x32_bf16 v[96:99], v[172:175], v[188:191], v[96:99]
	v_mfma_f32_16x16x32_bf16 v[84:87], v[164:167], v[200:203], v[84:87]
	v_mfma_f32_16x16x32_bf16 v[80:83], v[172:175], v[200:203], v[80:83]
	ds_read_b128 v[246:249], v143 offset:56320
	v_mfma_f32_16x16x32_bf16 v[68:71], v[164:167], v[208:211], v[68:71]
	v_mfma_f32_16x16x32_bf16 v[64:67], v[172:175], v[208:211], v[64:67]
	s_setprio 0
	s_barrier
	s_nop 0
	s_add_u32 s36, s36, 0xfffc0080
	s_addc_u32 s37, s37, -1
	s_add_u32 s34, s34, 0x80
	s_addc_u32 s35, s35, 0
	s_add_i32 m0, s54, s39
	s_nop 0
	global_load_lds_dwordx4 v192, s[34:35]
	s_add_i32 m0, m0, 0x2000
	s_nop 0
	global_load_lds_dwordx4 v128, s[34:35]
	s_add_u32 s34, s34, 0x40000
	s_addc_u32 s35, s35, 0
	s_add_i32 m0, s55, s39
	s_nop 0
	global_load_lds_dwordx4 v192, s[34:35]
	s_add_i32 m0, m0, 0x2000
	s_nop 0
	global_load_lds_dwordx4 v128, s[34:35]
	s_mov_b32 m0, s44
	s_nop 0
	global_load_lds_dwordx4 v132, s[36:37]
	s_mov_b32 m0, s45
	s_nop 0
	global_load_lds_dwordx4 v130, s[36:37]
	s_waitcnt vmcnt(8)
	s_waitcnt lgkmcnt(0)
	s_barrier
	s_setprio 1
	s_waitcnt lgkmcnt(0)
	v_mfma_f32_16x16x32_bf16 v[60:63], v[144:147], v[212:215], v[60:63]
	v_mfma_f32_16x16x32_bf16 v[56:59], v[152:155], v[212:215], v[56:59]
	ds_read_b128 v[176:179], v143
	v_mfma_f32_16x16x32_bf16 v[44:47], v[144:147], v[220:223], v[44:47]
	v_mfma_f32_16x16x32_bf16 v[40:43], v[152:155], v[220:223], v[40:43]
	v_mfma_f32_16x16x32_bf16 v[28:31], v[144:147], v[232:235], v[28:31]
	v_mfma_f32_16x16x32_bf16 v[24:27], v[152:155], v[232:235], v[24:27]
	ds_read_b128 v[180:183], v143 offset:1024
	v_mfma_f32_16x16x32_bf16 v[12:15], v[144:147], v[242:245], v[12:15]
	v_mfma_f32_16x16x32_bf16 v[8:11], v[152:155], v[242:245], v[8:11]
	v_mfma_f32_16x16x32_bf16 v[60:63], v[148:151], v[216:219], v[60:63]
	v_mfma_f32_16x16x32_bf16 v[56:59], v[156:159], v[216:219], v[56:59]
	ds_read_b128 v[184:187], v143 offset:2048
	v_mfma_f32_16x16x32_bf16 v[44:47], v[148:151], v[224:227], v[44:47]
	v_mfma_f32_16x16x32_bf16 v[40:43], v[156:159], v[224:227], v[40:43]
	v_mfma_f32_16x16x32_bf16 v[28:31], v[148:151], v[238:241], v[28:31]
	v_mfma_f32_16x16x32_bf16 v[24:27], v[156:159], v[238:241], v[24:27]
	ds_read_b128 v[188:191], v143 offset:3072
	v_mfma_f32_16x16x32_bf16 v[12:15], v[148:151], v[246:249], v[12:15]
	v_mfma_f32_16x16x32_bf16 v[8:11], v[156:159], v[246:249], v[8:11]
	s_setprio 0
	s_setprio 1
	v_mfma_f32_16x16x32_bf16 v[52:55], v[160:163], v[212:215], v[52:55]
	v_mfma_f32_16x16x32_bf16 v[48:51], v[168:171], v[212:215], v[48:51]
	ds_read_b128 v[196:199], v143 offset:4096
	v_mfma_f32_16x16x32_bf16 v[36:39], v[160:163], v[220:223], v[36:39]
	v_mfma_f32_16x16x32_bf16 v[32:35], v[168:171], v[220:223], v[32:35]
	v_mfma_f32_16x16x32_bf16 v[20:23], v[160:163], v[232:235], v[20:23]
	v_mfma_f32_16x16x32_bf16 v[16:19], v[168:171], v[232:235], v[16:19]
	ds_read_b128 v[200:203], v143 offset:5120
	v_mfma_f32_16x16x32_bf16 v[4:7], v[160:163], v[242:245], v[4:7]
	v_mfma_f32_16x16x32_bf16 v[0:3], v[168:171], v[242:245], v[0:3]
	v_mfma_f32_16x16x32_bf16 v[52:55], v[164:167], v[216:219], v[52:55]
	v_mfma_f32_16x16x32_bf16 v[48:51], v[172:175], v[216:219], v[48:51]
	ds_read_b128 v[204:207], v143 offset:6144
	v_mfma_f32_16x16x32_bf16 v[36:39], v[164:167], v[224:227], v[36:39]
	v_mfma_f32_16x16x32_bf16 v[32:35], v[172:175], v[224:227], v[32:35]
	v_mfma_f32_16x16x32_bf16 v[20:23], v[164:167], v[238:241], v[20:23]
	v_mfma_f32_16x16x32_bf16 v[16:19], v[172:175], v[238:241], v[16:19]
	ds_read_b128 v[208:211], v143 offset:7168
	v_mfma_f32_16x16x32_bf16 v[4:7], v[164:167], v[246:249], v[4:7]
	v_mfma_f32_16x16x32_bf16 v[0:3], v[172:175], v[246:249], v[0:3]
	s_setprio 0
	s_barrier
	s_add_i32 s53, s53, 2
	s_add_u32 s51, s51, 0x100
	s_addc_u32 s52, s52, 0
	s_add_u32 s30, s30, 0x100
	s_addc_u32 s31, s31, 0
	s_cmp_gt_u32 s53, 13
	s_cbranch_scc0 .Llag_574
.Llag_exit_574:
	s_waitcnt lgkmcnt(0)
.Lpeel_exit_574:
	s_and_b64 vcc, exec, s[20:21]
	s_cbranch_vccz .LBB0_577
	s_barrier
